# postA 2a transposes: XCD-aware unit start (slab transposed by the XCD whose stage-1 DFT tiles read it)
# baseline (speedup 1.0000x reference)
.LBB0_382:
	v_readlane_b32 s4, v254, 32
	s_waitcnt lgkmcnt(0)
	s_add_u32 s40, s54, 0x21e24000
	v_readlane_b32 s5, v254, 33
	s_addc_u32 s41, s55, 0
	s_andn2_b64 vcc, exec, s[4:5]
	v_lshlrev_b32_e32 v7, 3, v145
	v_add_u32_e32 v15, 0x200, v145
	v_add_u32_e32 v16, 0x400, v145
	v_add_u32_e32 v17, 0x600, v145
	v_add_u32_e32 v18, 0x800, v145
	v_add_u32_e32 v19, 0xa00, v145
	v_add_u32_e32 v20, 0xc00, v145
	v_add_u32_e32 v21, 0xe00, v145
	s_cbranch_vccnz .LBB0_385
	v_bfe_u32 v6, v145, 3, 6
	v_and_b32_e32 v2, 56, v7
	v_lshlrev_b32_e32 v4, 10, v2
	v_lshlrev_b32_e32 v5, 4, v6
	v_and_b32_e32 v3, 3, v145
	v_add3_u32 v4, 0, v4, v5
	v_lshl_add_u32 v22, v3, 2, v4
	v_bitop3_b32 v3, v145, 1, 3 bitop3:0x6c
	v_lshl_add_u32 v23, v3, 2, v4
	v_bitop3_b32 v3, v145, 2, 3 bitop3:0x6c
	v_lshrrev_b32_e32 v5, 4, v145
	v_lshl_add_u32 v24, v3, 2, v4
	v_bitop3_b32 v3, v145, 3, v145 bitop3:0xc
	s_add_u32 s6, s54, 0x31d24000
	v_and_b32_e32 v13, 2, v5
	v_lshlrev_b32_e32 v5, 4, v145
	v_lshl_add_u32 v25, v3, 2, v4
	v_lshlrev_b32_e32 v3, 4, v15
	v_lshlrev_b32_e32 v4, 4, v16
	v_lshlrev_b32_e32 v8, 4, v17
	v_lshlrev_b32_e32 v9, 4, v18
	v_lshlrev_b32_e32 v10, 4, v19
	v_lshlrev_b32_e32 v11, 4, v20
	v_lshlrev_b32_e32 v40, 4, v21
	s_addc_u32 s7, s55, 0
	v_and_b32_e32 v12, 31, v145
	v_ashrrev_i32_e32 v14, 6, v145
	v_ashrrev_i32_e32 v26, 6, v15
	v_ashrrev_i32_e32 v27, 6, v16
	v_ashrrev_i32_e32 v28, 6, v17
	v_ashrrev_i32_e32 v29, 6, v18
	v_ashrrev_i32_e32 v30, 6, v19
	v_ashrrev_i32_e32 v31, 6, v20
	v_ashrrev_i32_e32 v32, 6, v21
	s_lshl_b32 s8, s74, 6
	v_lshlrev_b32_e32 v98, 1, v2
	v_add_u32_e32 v33, 0, v5
	v_add_u32_e32 v34, 0, v3
	v_add_u32_e32 v35, 0, v4
	v_add_u32_e32 v36, 0, v8
	v_add_u32_e32 v37, 0, v9
	v_add_u32_e32 v38, 0, v10
	v_add_u32_e32 v39, 0, v11
	v_add_u32_e32 v40, 0, v40
	v_readlane_b32 s9, v254, 59
	s_mov_b32 s20, s2
	s_cmp_lg_u32 s74, 0x100
	s_cbranch_scc1 .LpA2_nomap
	s_lshr_b32 s100, s2, 3
	s_and_b32 s101, s100, 3
	s_lshl_b32 s20, s101, 6
	s_lshr_b32 s100, s100, 2
	s_and_b32 s101, s100, 3
	s_add_i32 s20, s20, s101
	s_lshr_b32 s100, s100, 2
	s_lshl_b32 s100, s100, 3
	s_add_i32 s20, s20, s100
	s_and_b32 s100, s2, 1
	s_lshl_b32 s100, s100, 2
	s_add_i32 s20, s20, s100
	s_bfe_u32 s100, s2, 0x20001
	s_lshl_b32 s100, s100, 4
	s_add_i32 s20, s20, s100
	s_lshl_b32 s9, s20, 6
.LpA2_nomap:
.LBB0_384:
	s_ashr_i32 s4, s20, 6
	s_bfe_u32 s10, s20, 0x20004
	s_ashr_i32 s5, s4, 31
	s_lshl_b32 s11, s10, 12
	s_lshl_b64 s[36:37], s[4:5], 9
	s_add_u32 s5, s36, s11
	v_or_b32_e32 v4, s5, v6
	v_mov_b64_e32 v[2:3], s[40:41]
	s_addc_u32 s11, s37, 0
	s_and_b32 s21, s9, 0x3c0
	v_mad_u64_u32 v[2:3], s[36:37], v4, s29, v[2:3]
	v_mad_i32_i24 v3, s11, v227, v3
	s_lshl_b32 s52, s21, 1
	v_lshl_add_u64 v[2:3], v[2:3], 0, s[52:53]
	v_lshl_add_u64 v[42:43], v[2:3], 0, v[98:99]
	s_mov_b32 s5, 0xa0000
	v_add_co_u32_e32 v8, vcc, s5, v42
	global_load_dwordx4 v[2:5], v[42:43], off offset:3072
	s_nop 0
	v_addc_co_u32_e32 v9, vcc, 0, v43, vcc
	global_load_dwordx4 v[8:11], v[8:9], off offset:3072
	s_mov_b32 s5, 0x140000
	s_lshl_b32 s4, s4, 3
	s_waitcnt vmcnt(0)
	v_and_b32_e32 v41, 0xffff, v2
	v_lshrrev_b32_e32 v2, 16, v2
	v_lshl_or_b32 v41, v8, 16, v41
	v_and_or_b32 v2, v8, s35, v2
	ds_write2st64_b32 v22, v41, v2 offset1:4
	v_and_b32_e32 v2, 0xffff, v3
	v_lshrrev_b32_e32 v3, 16, v3
	v_lshl_or_b32 v2, v9, 16, v2
	v_and_or_b32 v3, v9, s35, v3
	ds_write2st64_b32 v22, v2, v3 offset0:8 offset1:12
	v_and_b32_e32 v2, 0xffff, v4
	v_lshrrev_b32_e32 v3, 16, v4
	v_lshl_or_b32 v2, v10, 16, v2
	v_and_or_b32 v3, v10, s35, v3
	ds_write2st64_b32 v22, v2, v3 offset0:16 offset1:20
	v_and_b32_e32 v2, 0xffff, v5
	v_lshrrev_b32_e32 v3, 16, v5
	v_lshl_or_b32 v2, v11, 16, v2
	v_and_or_b32 v3, v11, s35, v3
	ds_write2st64_b32 v22, v2, v3 offset0:24 offset1:28
	v_add_co_u32_e32 v2, vcc, s5, v42
	s_mov_b32 s5, 0x1e0000
	s_nop 0
	v_addc_co_u32_e32 v3, vcc, 0, v43, vcc
	v_add_co_u32_e32 v8, vcc, s5, v42
	global_load_dwordx4 v[2:5], v[2:3], off offset:3072
	s_nop 0
	v_addc_co_u32_e32 v9, vcc, 0, v43, vcc
	global_load_dwordx4 v[8:11], v[8:9], off offset:3072
	s_mov_b32 s5, 0x280000
	s_waitcnt vmcnt(1)
	v_and_b32_e32 v41, 0xffff, v2
	v_lshrrev_b32_e32 v2, 16, v2
	s_waitcnt vmcnt(0)
	v_lshl_or_b32 v41, v8, 16, v41
	v_and_or_b32 v2, v8, s35, v2
	ds_write2st64_b32 v23, v41, v2 offset1:4
	v_and_b32_e32 v2, 0xffff, v3
	v_lshrrev_b32_e32 v3, 16, v3
	v_lshl_or_b32 v2, v9, 16, v2
	v_and_or_b32 v3, v9, s35, v3
	ds_write2st64_b32 v23, v2, v3 offset0:8 offset1:12
	v_and_b32_e32 v2, 0xffff, v4
	v_lshrrev_b32_e32 v3, 16, v4
	v_lshl_or_b32 v2, v10, 16, v2
	v_and_or_b32 v3, v10, s35, v3
	ds_write2st64_b32 v23, v2, v3 offset0:16 offset1:20
	v_and_b32_e32 v2, 0xffff, v5
	v_lshrrev_b32_e32 v3, 16, v5
	v_lshl_or_b32 v2, v11, 16, v2
	v_and_or_b32 v3, v11, s35, v3
	ds_write2st64_b32 v23, v2, v3 offset0:24 offset1:28
	v_add_co_u32_e32 v2, vcc, s5, v42
	s_mov_b32 s5, 0x320000
	s_nop 0
	v_addc_co_u32_e32 v3, vcc, 0, v43, vcc
	v_add_co_u32_e32 v8, vcc, s5, v42
	global_load_dwordx4 v[2:5], v[2:3], off offset:3072
	s_nop 0
	v_addc_co_u32_e32 v9, vcc, 0, v43, vcc
	global_load_dwordx4 v[8:11], v[8:9], off offset:3072
	s_mov_b32 s5, 0x3c0000
	s_waitcnt vmcnt(1)
	v_and_b32_e32 v41, 0xffff, v2
	v_lshrrev_b32_e32 v2, 16, v2
	s_waitcnt vmcnt(0)
	v_lshl_or_b32 v41, v8, 16, v41
	v_and_or_b32 v2, v8, s35, v2
	ds_write2st64_b32 v24, v41, v2 offset1:4
	v_and_b32_e32 v2, 0xffff, v3
	v_lshrrev_b32_e32 v3, 16, v3
	v_lshl_or_b32 v2, v9, 16, v2
	v_and_or_b32 v3, v9, s35, v3
	ds_write2st64_b32 v24, v2, v3 offset0:8 offset1:12
	v_and_b32_e32 v2, 0xffff, v4
	v_lshrrev_b32_e32 v3, 16, v4
	v_lshl_or_b32 v2, v10, 16, v2
	v_and_or_b32 v3, v10, s35, v3
	ds_write2st64_b32 v24, v2, v3 offset0:16 offset1:20
	v_and_b32_e32 v2, 0xffff, v5
	v_lshrrev_b32_e32 v3, 16, v5
	v_lshl_or_b32 v2, v11, 16, v2
	v_and_or_b32 v3, v11, s35, v3
	ds_write2st64_b32 v24, v2, v3 offset0:24 offset1:28
	v_add_co_u32_e32 v2, vcc, s5, v42
	s_mov_b32 s5, 0x460000
	s_nop 0
	v_addc_co_u32_e32 v3, vcc, 0, v43, vcc
	v_add_co_u32_e32 v8, vcc, s5, v42
	global_load_dwordx4 v[2:5], v[2:3], off offset:3072
	s_nop 0
	v_addc_co_u32_e32 v9, vcc, 0, v43, vcc
	global_load_dwordx4 v[8:11], v[8:9], off offset:3072
	s_ashr_i32 s5, s4, 31
	s_lshl_b64 s[4:5], s[4:5], 1
	s_add_u32 s4, s6, s4
	s_addc_u32 s5, s7, s5
	s_add_i32 s20, s20, s74
	s_add_i32 s9, s9, s8
	s_cmpk_gt_i32 s20, 0x1ff
	s_waitcnt vmcnt(1)
	v_and_b32_e32 v41, 0xffff, v2
	v_lshrrev_b32_e32 v2, 16, v2
	s_waitcnt vmcnt(0)
	v_lshl_or_b32 v41, v8, 16, v41
	v_and_or_b32 v2, v8, s35, v2
	ds_write2st64_b32 v25, v41, v2 offset1:4
	v_and_b32_e32 v2, 0xffff, v3
	v_lshrrev_b32_e32 v3, 16, v3
	v_lshl_or_b32 v2, v9, 16, v2
	v_and_or_b32 v3, v9, s35, v3
	ds_write2st64_b32 v25, v2, v3 offset0:8 offset1:12
	v_and_b32_e32 v2, 0xffff, v4
	v_lshrrev_b32_e32 v3, 16, v4
	v_lshl_or_b32 v2, v10, 16, v2
	v_and_or_b32 v3, v10, s35, v3
	ds_write2st64_b32 v25, v2, v3 offset0:16 offset1:20
	v_and_b32_e32 v2, 0xffff, v5
	v_lshrrev_b32_e32 v3, 16, v5
	v_add_u32_e32 v9, s21, v14
	v_lshl_or_b32 v2, v11, 16, v2
	v_and_or_b32 v3, v11, s35, v3
	v_lshl_or_b32 v41, s10, 14, v12
	v_ashrrev_i32_e32 v8, 9, v9
	v_lshlrev_b32_e32 v9, 5, v9
	ds_write2st64_b32 v25, v2, v3 offset0:24 offset1:28
	s_waitcnt lgkmcnt(0)
	s_barrier
	ds_read_b128 v[2:5], v33
	v_and_or_b32 v9, v9, s31, v41
	v_lshl_or_b32 v10, v9, 2, v13
	v_mov_b32_e32 v11, v99
	v_ashrrev_i32_e32 v9, 31, v8
	v_lshl_add_u64 v[8:9], v[10:11], 0, v[8:9]
	v_lshlrev_b64 v[8:9], 7, v[8:9]
	v_lshl_add_u64 v[8:9], s[4:5], 0, v[8:9]
	s_waitcnt lgkmcnt(0)
	global_store_dwordx4 v[8:9], v[2:5], off
	v_add_u32_e32 v9, s21, v26
	ds_read_b128 v[2:5], v34
	v_ashrrev_i32_e32 v8, 9, v9
	v_lshlrev_b32_e32 v9, 5, v9
	v_and_or_b32 v9, v9, s31, v41
	v_lshl_or_b32 v10, v9, 2, v13
	v_ashrrev_i32_e32 v9, 31, v8
	v_lshl_add_u64 v[8:9], v[10:11], 0, v[8:9]
	v_lshlrev_b64 v[8:9], 7, v[8:9]
	s_waitcnt lgkmcnt(0)
	v_pk_mov_b32 v[4:5], v[4:5], v[4:5] op_sel:[1,0]
	v_pk_mov_b32 v[2:3], v[2:3], v[2:3] op_sel:[1,0]
	v_lshl_add_u64 v[8:9], s[4:5], 0, v[8:9]
	global_store_dwordx4 v[8:9], v[2:5], off
	ds_read_b128 v[2:5], v35
	s_waitcnt lgkmcnt(0)
	v_mov_b32_e32 v11, v3
	v_add_u32_e32 v3, s21, v27
	v_mov_b32_e32 v10, v2
	v_ashrrev_i32_e32 v2, 9, v3
	v_lshlrev_b32_e32 v3, 5, v3
	v_and_or_b32 v3, v3, s31, v41
	v_mov_b32_e32 v8, v4
	v_mov_b32_e32 v9, v5
	v_lshl_or_b32 v4, v3, 2, v13
	v_mov_b32_e32 v5, v99
	v_ashrrev_i32_e32 v3, 31, v2
	v_lshl_add_u64 v[2:3], v[4:5], 0, v[2:3]
	v_lshlrev_b64 v[2:3], 7, v[2:3]
	v_lshl_add_u64 v[2:3], s[4:5], 0, v[2:3]
	global_store_dwordx4 v[2:3], v[8:11], off
	ds_read_b128 v[2:5], v36
	s_waitcnt lgkmcnt(0)
	v_pk_mov_b32 v[10:11], v[2:3], v[2:3] op_sel:[1,0]
	v_add_u32_e32 v3, s21, v28
	v_ashrrev_i32_e32 v2, 9, v3
	v_lshlrev_b32_e32 v3, 5, v3
	v_and_or_b32 v3, v3, s31, v41
	v_pk_mov_b32 v[8:9], v[4:5], v[4:5] op_sel:[1,0]
	v_lshl_or_b32 v4, v3, 2, v13
	v_mov_b32_e32 v5, v99
	v_ashrrev_i32_e32 v3, 31, v2
	v_lshl_add_u64 v[2:3], v[4:5], 0, v[2:3]
	v_lshlrev_b64 v[2:3], 7, v[2:3]
	v_lshl_add_u64 v[2:3], s[4:5], 0, v[2:3]
	global_store_dwordx4 v[2:3], v[8:11], off
	ds_read_b128 v[2:5], v37
	s_nop 0
	v_add_u32_e32 v9, s21, v29
	v_ashrrev_i32_e32 v8, 9, v9
	v_lshlrev_b32_e32 v9, 5, v9
	v_and_or_b32 v9, v9, s31, v41
	v_lshl_or_b32 v10, v9, 2, v13
	v_mov_b32_e32 v11, v99
	v_ashrrev_i32_e32 v9, 31, v8
	v_lshl_add_u64 v[8:9], v[10:11], 0, v[8:9]
	v_lshlrev_b64 v[8:9], 7, v[8:9]
	v_lshl_add_u64 v[8:9], s[4:5], 0, v[8:9]
	s_waitcnt lgkmcnt(0)
	global_store_dwordx4 v[8:9], v[2:5], off
	v_add_u32_e32 v9, s21, v30
	ds_read_b128 v[2:5], v38
	v_ashrrev_i32_e32 v8, 9, v9
	v_lshlrev_b32_e32 v9, 5, v9
	v_and_or_b32 v9, v9, s31, v41
	v_lshl_or_b32 v10, v9, 2, v13
	v_ashrrev_i32_e32 v9, 31, v8
	v_lshl_add_u64 v[8:9], v[10:11], 0, v[8:9]
	v_lshlrev_b64 v[8:9], 7, v[8:9]
	s_waitcnt lgkmcnt(0)
	v_pk_mov_b32 v[4:5], v[4:5], v[4:5] op_sel:[1,0]
	v_pk_mov_b32 v[2:3], v[2:3], v[2:3] op_sel:[1,0]
	v_lshl_add_u64 v[8:9], s[4:5], 0, v[8:9]
	global_store_dwordx4 v[8:9], v[2:5], off
	ds_read_b128 v[2:5], v39
	s_waitcnt lgkmcnt(0)
	v_mov_b32_e32 v11, v3
	v_add_u32_e32 v3, s21, v31
	v_mov_b32_e32 v10, v2
	v_ashrrev_i32_e32 v2, 9, v3
	v_lshlrev_b32_e32 v3, 5, v3
	v_and_or_b32 v3, v3, s31, v41
	v_mov_b32_e32 v8, v4
	v_mov_b32_e32 v9, v5
	v_lshl_or_b32 v4, v3, 2, v13
	v_mov_b32_e32 v5, v99
	v_ashrrev_i32_e32 v3, 31, v2
	v_lshl_add_u64 v[2:3], v[4:5], 0, v[2:3]
	v_lshlrev_b64 v[2:3], 7, v[2:3]
	v_lshl_add_u64 v[2:3], s[4:5], 0, v[2:3]
	global_store_dwordx4 v[2:3], v[8:11], off
	ds_read_b128 v[8:11], v40
	s_waitcnt lgkmcnt(0)
	v_pk_mov_b32 v[4:5], v[8:9], v[8:9] op_sel:[1,0]
	v_add_u32_e32 v9, s21, v32
	v_ashrrev_i32_e32 v8, 9, v9
	v_lshlrev_b32_e32 v9, 5, v9
	v_and_or_b32 v9, v9, s31, v41
	v_pk_mov_b32 v[2:3], v[10:11], v[10:11] op_sel:[1,0]
	v_lshl_or_b32 v10, v9, 2, v13
	v_mov_b32_e32 v11, v99
	v_ashrrev_i32_e32 v9, 31, v8
	v_lshl_add_u64 v[8:9], v[10:11], 0, v[8:9]
	v_lshlrev_b64 v[8:9], 7, v[8:9]
	v_lshl_add_u64 v[8:9], s[4:5], 0, v[8:9]
	global_store_dwordx4 v[8:9], v[2:5], off
	s_barrier
	s_cbranch_scc0 .LBB0_384
